# de-serialized load chains: P0 g_pre hoist, MLA unit prologue rope-Q loads issued together, P2 latent-norm CKV load hoisted
# speedup vs baseline: 1.0100x; 1.0083x over previous
; __device__ __forceinline__ unsigned pk2(float lo, float hi) { return f2bf(lo) | (f2bf(hi) << 16); }
; #define lane lane_id()
; __global__ void __launch_bounds__(NWAVES * 64, 2) hybrid_fwd(Args args) {
;     ...
;         for (int m = gw; m < MR; m += NGW) {
;             { v4u* p = (v4u*)(CQ + (size_t)m * Q_LORA) + lane; v4u v[3]; float s = 0.f;
; #pragma unroll
;                 for (int j = 0; j < 3; ++j) { v[j] = p[64 * j];
; #pragma unroll
;                     for (int e = 0; e < 4; ++e) { const float a = bflo(v[j][e]), b = bfhi(v[j][e]); s += a * a + b * b; } }
;                 const float rstd = 1.f / sqrtf(wave_sum(s) * (1.f / Q_LORA) + RMS_EPS);
; #pragma unroll
;                 for (int j = 0; j < 3; ++j) { v4u o;
; #pragma unroll
;                     for (int e = 0; e < 4; ++e) { const f32x4 gg = gq[2 * j + (e >> 1)];
;                         o[e] = pk2(bflo(v[j][e]) * rstd * gg[(e & 1) * 2], bfhi(v[j][e]) * rstd * gg[(e & 1) * 2 + 1]); }
;                     p[64 * j] = o; } }
;             { v4u* p = (v4u*)(CKV + (size_t)m * KV_LORA) + lane; v4u v = p[0]; float s = 0.f;
.LBB0_480:
	v_and_b32_e32 v37, 64, v34
	v_xor_b32_e32 v38, 1, v34
	v_add_u32_e32 v37, 64, v37
	v_xor_b32_e32 v39, 2, v34
	v_cmp_lt_i32_e32 vcc, v38, v37
	v_xor_b32_e32 v40, 4, v34
	v_xor_b32_e32 v41, 8, v34
	v_cndmask_b32_e32 v50, v34, v38, vcc
	v_cmp_lt_i32_e32 vcc, v39, v37
	v_xor_b32_e32 v42, 16, v34
	v_mbcnt_lo_u32_b32 v30, -1, 0
	v_mbcnt_hi_u32_b32 v30, -1, v30
	v_xor_b32_e32 v43, 32, v34
	v_cndmask_b32_e32 v51, v34, v39, vcc
	v_cmp_lt_i32_e32 vcc, v40, v37
	v_lshlrev_b32_e32 v100, 4, v30
	v_ashrrev_i32_e32 v31, 31, v30
	v_lshl_add_u64 v[30:31], v[30:31], 4, s[52:53]
	v_cndmask_b32_e32 v52, v34, v40, vcc
	v_cmp_lt_i32_e32 vcc, v41, v37
	v_lshlrev_b32_e32 v76, 2, v52
	v_lshlrev_b32_e32 v74, 2, v50
	v_cndmask_b32_e32 v53, v34, v41, vcc
	v_cmp_lt_i32_e32 vcc, v42, v37
	v_lshlrev_b32_e32 v77, 2, v53
	v_lshlrev_b32_e32 v75, 2, v51
	v_cndmask_b32_e32 v54, v34, v42, vcc
	v_cmp_lt_i32_e32 vcc, v43, v37
	v_lshlrev_b32_e32 v78, 2, v54
	s_add_i32 s17, s17, s68
	v_cndmask_b32_e32 v37, v34, v43, vcc
	global_load_dwordx4 v[38:41], v[30:31], off
	global_load_dwordx4 v[42:45], v[30:31], off offset:-2048
	global_load_dwordx4 v[46:49], v[30:31], off offset:-1024
	global_load_dwordx4 v[96:99], v100, s[38:39]
	v_lshlrev_b32_e32 v37, 2, v37
	s_waitcnt vmcnt(2)
	v_lshlrev_b32_e32 v61, 16, v39
	s_waitcnt vmcnt(1)
	v_lshlrev_b32_e32 v53, 16, v43
	v_lshlrev_b32_e32 v52, 16, v42
	v_and_b32_e32 v43, 0xffff0000, v43
	v_and_b32_e32 v42, 0xffff0000, v42
	v_lshlrev_b32_e32 v55, 16, v45
	v_lshlrev_b32_e32 v54, 16, v44
	v_and_b32_e32 v45, 0xffff0000, v45
	v_and_b32_e32 v44, 0xffff0000, v44
	v_pk_mul_f32 v[64:65], v[42:43], v[42:43]
	v_pk_mul_f32 v[66:67], v[44:45], v[44:45]
	v_pk_fma_f32 v[64:65], v[52:53], v[52:53], v[64:65]
	s_waitcnt vmcnt(0)
	v_lshlrev_b32_e32 v57, 16, v47
	v_lshlrev_b32_e32 v56, 16, v46
	v_and_b32_e32 v47, 0xffff0000, v47
	v_and_b32_e32 v46, 0xffff0000, v46
	v_pk_fma_f32 v[66:67], v[54:55], v[54:55], v[66:67]
	v_add_f32_e32 v64, v64, v65
	v_pk_mul_f32 v[68:69], v[46:47], v[46:47]
	v_add_f32_e32 v64, v64, v66
	v_lshlrev_b32_e32 v59, 16, v49
	v_lshlrev_b32_e32 v58, 16, v48
	v_and_b32_e32 v49, 0xffff0000, v49
	v_and_b32_e32 v48, 0xffff0000, v48
	v_pk_fma_f32 v[68:69], v[56:57], v[56:57], v[68:69]
	v_add_f32_e32 v64, v64, v67
	v_pk_mul_f32 v[70:71], v[48:49], v[48:49]
	v_add_f32_e32 v64, v64, v68
	v_lshlrev_b32_e32 v60, 16, v38
	v_and_b32_e32 v39, 0xffff0000, v39
	v_and_b32_e32 v38, 0xffff0000, v38
	v_pk_fma_f32 v[70:71], v[58:59], v[58:59], v[70:71]
	v_add_f32_e32 v64, v64, v69
	v_pk_mul_f32 v[72:73], v[38:39], v[38:39]
	v_add_f32_e32 v64, v64, v70
	v_lshlrev_b32_e32 v51, 16, v41
	v_lshlrev_b32_e32 v50, 16, v40
	v_and_b32_e32 v41, 0xffff0000, v41
	v_and_b32_e32 v40, 0xffff0000, v40
	v_pk_fma_f32 v[72:73], v[60:61], v[60:61], v[72:73]
	v_add_f32_e32 v64, v64, v71
	v_pk_mul_f32 v[62:63], v[40:41], v[40:41]
	v_add_f32_e32 v64, v64, v72
	v_pk_fma_f32 v[62:63], v[50:51], v[50:51], v[62:63]
	v_add_f32_e32 v64, v64, v73
	v_add_f32_e32 v62, v64, v62
	v_add_f32_e32 v62, v62, v63
	ds_bpermute_b32 v63, v74, v62
	s_waitcnt lgkmcnt(0)
	v_add_f32_e32 v62, v62, v63
	ds_bpermute_b32 v63, v75, v62
	s_waitcnt lgkmcnt(0)
	v_add_f32_e32 v62, v62, v63
	ds_bpermute_b32 v63, v76, v62
	s_waitcnt lgkmcnt(0)
	v_add_f32_e32 v62, v62, v63
	ds_bpermute_b32 v63, v77, v62
	s_waitcnt lgkmcnt(0)
	v_add_f32_e32 v62, v62, v63
	ds_bpermute_b32 v63, v78, v62
	s_waitcnt lgkmcnt(0)
	v_add_f32_e32 v62, v62, v63
	ds_bpermute_b32 v63, v37, v62
	s_waitcnt lgkmcnt(0)
	v_add_f32_e32 v62, v62, v63
	v_fmamk_f32 v62, v62, 0x3a2aaaab, v35
	v_mul_f32_e32 v63, 0x4f800000, v62
	v_cmp_gt_f32_e32 vcc, s5, v62
	s_nop 1
	v_cndmask_b32_e32 v62, v62, v63, vcc
	v_sqrt_f32_e32 v63, v62
	s_nop 0
	v_add_u32_e32 v64, -1, v63
	v_add_u32_e32 v65, 1, v63
	v_fma_f32 v66, -v64, v63, v62
	v_fma_f32 v67, -v65, v63, v62
	v_cmp_ge_f32_e64 s[2:3], 0, v66
	s_nop 1
	v_cndmask_b32_e64 v63, v63, v64, s[2:3]
	v_cmp_lt_f32_e64 s[2:3], 0, v67
	s_nop 1
	v_cndmask_b32_e64 v63, v63, v65, s[2:3]
	v_mul_f32_e32 v64, 0x37800000, v63
	v_cndmask_b32_e32 v63, v63, v64, vcc
	v_cmp_class_f32_e32 vcc, v62, v36
	s_nop 1
	v_cndmask_b32_e32 v62, v63, v62, vcc
	v_div_scale_f32 v63, s[2:3], v62, v62, 1.0
	v_rcp_f32_e32 v65, v63
	v_div_scale_f32 v64, vcc, 1.0, v62, 1.0
	v_fma_f32 v66, -v63, v65, 1.0
	v_fmac_f32_e32 v65, v66, v65
	v_mul_f32_e32 v66, v64, v65
	v_fma_f32 v67, -v63, v66, v64
	v_fmac_f32_e32 v66, v67, v65
	v_fma_f32 v63, -v63, v66, v64
	v_div_fmas_f32 v63, v63, v65, v66
	v_div_fixup_f32 v62, v63, v62, 1.0
	v_pk_mul_f32 v[52:53], v[62:63], v[52:53] op_sel_hi:[0,1]
	v_pk_mul_f32 v[54:55], v[62:63], v[54:55] op_sel_hi:[0,1]
	v_pk_mul_f32 v[42:43], v[62:63], v[42:43] op_sel_hi:[0,1]
	v_pk_mul_f32 v[44:45], v[62:63], v[44:45] op_sel_hi:[0,1]
	v_pk_mul_f32 v[56:57], v[62:63], v[56:57] op_sel_hi:[0,1]
	v_pk_mul_f32 v[58:59], v[62:63], v[58:59] op_sel_hi:[0,1]
	v_pk_mul_f32 v[60:61], v[62:63], v[60:61] op_sel_hi:[0,1]
	v_pk_mul_f32 v[38:39], v[62:63], v[38:39] op_sel_hi:[0,1]
	v_pk_mul_f32 v[50:51], v[62:63], v[50:51] op_sel_hi:[0,1]
	v_pk_mul_f32 v[40:41], v[62:63], v[40:41] op_sel_hi:[0,1]
	v_pk_mul_f32 v[52:53], v[0:1], v[52:53]
	v_pk_mul_f32 v[54:55], v[4:5], v[54:55]
	v_pk_mul_f32 v[46:47], v[62:63], v[46:47] op_sel_hi:[0,1]
	v_pk_mul_f32 v[48:49], v[62:63], v[48:49] op_sel_hi:[0,1]
	v_pk_mul_f32 v[42:43], v[32:33], v[42:43]
	v_pk_mul_f32 v[44:45], v[2:3], v[44:45]
	v_pk_mul_f32 v[56:57], v[8:9], v[56:57]
	v_pk_mul_f32 v[58:59], v[12:13], v[58:59]
	v_pk_mul_f32 v[60:61], v[16:17], v[60:61]
	v_pk_mul_f32 v[38:39], v[14:15], v[38:39]
	v_pk_mul_f32 v[50:51], v[20:21], v[50:51]
	v_pk_mul_f32 v[40:41], v[18:19], v[40:41]
	v_bfe_u32 v66, v52, 16, 1
; __device__ __forceinline__ unsigned pk2(float lo, float hi) { return f2bf(lo) | (f2bf(hi) << 16); }
; #define lane lane_id()
; __global__ void __launch_bounds__(NWAVES * 64, 2) hybrid_fwd(Args args) {
;     ...
;                 for (int j = 0; j < 3; ++j) { v4u o;
; #pragma unroll
;                     for (int e = 0; e < 4; ++e) { const f32x4 gg = gq[2 * j + (e >> 1)];
;                         o[e] = pk2(bflo(v[j][e]) * rstd * gg[(e & 1) * 2], bfhi(v[j][e]) * rstd * gg[(e & 1) * 2 + 1]); }
;                     p[64 * j] = o; } }
;             { v4u* p = (v4u*)(CKV + (size_t)m * KV_LORA) + lane; v4u v = p[0]; float s = 0.f;
; #pragma unroll
;                 for (int e = 0; e < 4; ++e) { const float a = bflo(v[e]), b = bfhi(v[e]); s += a * a + b * b; }
;                 const float rstd = 1.f / sqrtf(wave_sum(s) * (1.f / KV_LORA) + RMS_EPS); v4u o;
; #pragma unroll
;                 for (int e = 0; e < 4; ++e) { const f32x4 gg = gk[e >> 1]; o[e] = pk2(bflo(v[e]) * rstd * gg[(e & 1) * 2], bfhi(v[e]) * rstd * gg[(e & 1) * 2 + 1]); }
;                 p[0] = o; }
	v_bfe_u32 v67, v53, 16, 1
	v_bfe_u32 v68, v54, 16, 1
	v_bfe_u32 v69, v55, 16, 1
	v_pk_mul_f32 v[46:47], v[6:7], v[46:47]
	v_pk_mul_f32 v[48:49], v[10:11], v[48:49]
	v_bfe_u32 v62, v45, 16, 1
	v_bfe_u32 v63, v44, 16, 1
	v_bfe_u32 v64, v43, 16, 1
	v_bfe_u32 v65, v42, 16, 1
	v_bfe_u32 v79, v56, 16, 1
	v_bfe_u32 v80, v57, 16, 1
	v_bfe_u32 v81, v58, 16, 1
	v_bfe_u32 v82, v59, 16, 1
	v_bfe_u32 v83, v41, 16, 1
	v_bfe_u32 v84, v40, 16, 1
	v_bfe_u32 v85, v39, 16, 1
	v_bfe_u32 v86, v38, 16, 1
	v_bfe_u32 v87, v60, 16, 1
	v_bfe_u32 v88, v61, 16, 1
	v_bfe_u32 v89, v50, 16, 1
	v_bfe_u32 v90, v51, 16, 1
	v_add3_u32 v55, v55, v69, s16
	v_add3_u32 v54, v54, v68, s16
	v_add3_u32 v53, v53, v67, s16
	v_add3_u32 v52, v52, v66, s16
	v_bfe_u32 v70, v49, 16, 1
	v_bfe_u32 v71, v48, 16, 1
	v_bfe_u32 v72, v47, 16, 1
	v_bfe_u32 v73, v46, 16, 1
	v_add3_u32 v42, v42, v65, s16
	v_add3_u32 v43, v43, v64, s16
	v_add3_u32 v44, v44, v63, s16
	v_add3_u32 v45, v45, v62, s16
	v_add3_u32 v59, v59, v82, s16
	v_add3_u32 v58, v58, v81, s16
	v_add3_u32 v57, v57, v80, s16
	v_add3_u32 v56, v56, v79, s16
	v_add3_u32 v62, v38, v86, s16
	v_add3_u32 v63, v39, v85, s16
	v_add3_u32 v64, v40, v84, s16
	v_add3_u32 v65, v41, v83, s16
	v_add3_u32 v38, v51, v90, s16
	v_add3_u32 v39, v50, v89, s16
	v_add3_u32 v40, v61, v88, s16
	v_add3_u32 v41, v60, v87, s16
	v_lshrrev_b32_e32 v50, 16, v52
	v_lshrrev_b32_e32 v51, 16, v53
	v_lshrrev_b32_e32 v52, 16, v54
	v_lshrrev_b32_e32 v53, 16, v55
	v_add3_u32 v46, v46, v73, s16
	v_add3_u32 v47, v47, v72, s16
	v_add3_u32 v48, v48, v71, s16
	v_add3_u32 v49, v49, v70, s16
	v_lshrrev_b32_e32 v54, 16, v56
	v_lshrrev_b32_e32 v55, 16, v57
	v_lshrrev_b32_e32 v56, 16, v58
	v_lshrrev_b32_e32 v57, 16, v59
	v_lshrrev_b32_e32 v58, 16, v41
	v_lshrrev_b32_e32 v59, 16, v40
	v_lshrrev_b32_e32 v60, 16, v39
	v_lshrrev_b32_e32 v61, 16, v38
	v_and_or_b32 v41, v45, s4, v53
	v_and_or_b32 v40, v44, s4, v52
	v_and_or_b32 v39, v43, s4, v51
	v_and_or_b32 v38, v42, s4, v50
	v_and_or_b32 v45, v49, s4, v57
	v_and_or_b32 v44, v48, s4, v56
	v_and_or_b32 v43, v47, s4, v55
	v_and_or_b32 v42, v46, s4, v54
	v_and_or_b32 v49, v65, s4, v61
	v_and_or_b32 v48, v64, s4, v60
	v_and_or_b32 v47, v63, s4, v59
	v_and_or_b32 v46, v62, s4, v58
	global_store_dwordx4 v[30:31], v[38:41], off offset:-2048
	global_store_dwordx4 v[30:31], v[42:45], off offset:-1024
	global_store_dwordx4 v[30:31], v[46:49], off
	v_mbcnt_lo_u32_b32 v30, -1, 0
	v_mbcnt_hi_u32_b32 v30, -1, v30
	s_nop 0
	v_ashrrev_i32_e32 v31, 31, v30
	v_lshl_add_u64 v[30:31], v[30:31], 4, s[38:39]
	s_add_u32 s38, s38, s46
	s_addc_u32 s39, s39, s47
	s_add_u32 s52, s52, s1
	s_addc_u32 s53, s53, s0
	s_cmpk_gt_i32 s17, 0x3fff
	v_mov_b32_e32 v38, v96
	v_mov_b32_e32 v39, v97
	v_mov_b32_e32 v40, v98
	v_mov_b32_e32 v41, v99
	v_lshlrev_b32_e32 v43, 16, v39
	v_lshlrev_b32_e32 v42, 16, v38
	v_and_b32_e32 v39, 0xffff0000, v39
	v_and_b32_e32 v38, 0xffff0000, v38
	v_lshlrev_b32_e32 v45, 16, v41
	v_lshlrev_b32_e32 v44, 16, v40
	v_and_b32_e32 v41, 0xffff0000, v41
	v_and_b32_e32 v40, 0xffff0000, v40
	v_pk_mul_f32 v[46:47], v[38:39], v[38:39]
	v_pk_mul_f32 v[48:49], v[40:41], v[40:41]
	v_pk_fma_f32 v[46:47], v[42:43], v[42:43], v[46:47]
	v_pk_fma_f32 v[48:49], v[44:45], v[44:45], v[48:49]
	v_add_f32_e32 v46, v46, v47
	v_add_f32_e32 v46, v46, v48
	v_add_f32_e32 v46, v46, v49
	ds_bpermute_b32 v47, v74, v46
	s_waitcnt lgkmcnt(0)
	v_add_f32_e32 v46, v46, v47
	ds_bpermute_b32 v47, v75, v46
	s_waitcnt lgkmcnt(0)
	v_add_f32_e32 v46, v46, v47
	ds_bpermute_b32 v47, v76, v46
	s_waitcnt lgkmcnt(0)
	v_add_f32_e32 v46, v46, v47
	ds_bpermute_b32 v47, v77, v46
	s_waitcnt lgkmcnt(0)
	v_add_f32_e32 v46, v46, v47
	ds_bpermute_b32 v47, v78, v46
	s_waitcnt lgkmcnt(0)
	v_add_f32_e32 v46, v46, v47
	ds_bpermute_b32 v37, v37, v46
	s_waitcnt lgkmcnt(0)
	v_add_f32_e32 v37, v46, v37
	v_fmamk_f32 v37, v37, 0x3b000000, v35
	v_mul_f32_e32 v46, 0x4f800000, v37
	v_cmp_gt_f32_e32 vcc, s5, v37
	s_nop 1
	v_cndmask_b32_e32 v37, v37, v46, vcc
	v_sqrt_f32_e32 v46, v37
	s_nop 0
	v_add_u32_e32 v47, -1, v46
	v_add_u32_e32 v48, 1, v46
	v_fma_f32 v49, -v47, v46, v37
	v_fma_f32 v50, -v48, v46, v37
	v_cmp_ge_f32_e64 s[2:3], 0, v49
	s_nop 1
	v_cndmask_b32_e64 v46, v46, v47, s[2:3]
	v_cmp_lt_f32_e64 s[2:3], 0, v50
	s_nop 1
	v_cndmask_b32_e64 v46, v46, v48, s[2:3]
	v_mul_f32_e32 v47, 0x37800000, v46
	v_cndmask_b32_e32 v46, v46, v47, vcc
	v_cmp_class_f32_e32 vcc, v37, v36
	s_nop 1
	v_cndmask_b32_e32 v37, v46, v37, vcc
	v_div_scale_f32 v46, s[2:3], v37, v37, 1.0
	v_rcp_f32_e32 v48, v46
	v_div_scale_f32 v47, vcc, 1.0, v37, 1.0
	v_fma_f32 v49, -v46, v48, 1.0
	v_fmac_f32_e32 v48, v49, v48
	v_mul_f32_e32 v49, v47, v48
	v_fma_f32 v50, -v46, v49, v47
	v_fmac_f32_e32 v49, v50, v48
	v_fma_f32 v46, -v46, v49, v47
	v_div_fmas_f32 v46, v46, v48, v49
	v_div_fixup_f32 v46, v46, v37, 1.0
	v_pk_mul_f32 v[42:43], v[46:47], v[42:43] op_sel_hi:[0,1]
	v_pk_mul_f32 v[44:45], v[46:47], v[44:45] op_sel_hi:[0,1]
	v_pk_mul_f32 v[40:41], v[46:47], v[40:41] op_sel_hi:[0,1]
	v_pk_mul_f32 v[38:39], v[46:47], v[38:39] op_sel_hi:[0,1]
	v_pk_mul_f32 v[42:43], v[42:43], v[24:25]
	v_pk_mul_f32 v[44:45], v[44:45], v[28:29]
	v_pk_mul_f32 v[40:41], v[40:41], v[26:27]
	v_pk_mul_f32 v[38:39], v[38:39], v[22:23]
	v_bfe_u32 v37, v41, 16, 1
	v_bfe_u32 v49, v42, 16, 1
	v_bfe_u32 v50, v43, 16, 1
	v_bfe_u32 v51, v44, 16, 1
	v_bfe_u32 v52, v45, 16, 1
	v_bfe_u32 v46, v40, 16, 1
	v_bfe_u32 v47, v39, 16, 1
	v_bfe_u32 v48, v38, 16, 1
	v_add3_u32 v37, v41, v37, s16
	v_add3_u32 v41, v45, v52, s16
	v_add3_u32 v44, v44, v51, s16
	v_add3_u32 v43, v43, v50, s16
	v_add3_u32 v42, v42, v49, s16
	v_add3_u32 v38, v38, v48, s16
	v_add3_u32 v39, v39, v47, s16
	v_add3_u32 v40, v40, v46, s16
	v_lshrrev_b32_e32 v42, 16, v42
	v_lshrrev_b32_e32 v43, 16, v43
	v_lshrrev_b32_e32 v44, 16, v44
	v_lshrrev_b32_e32 v41, 16, v41
	v_and_or_b32 v41, v37, s4, v41
	v_and_or_b32 v40, v40, s4, v44
	v_and_or_b32 v39, v39, s4, v43
	v_and_or_b32 v38, v38, s4, v42
	global_store_dwordx4 v[30:31], v[38:41], off
	s_cbranch_scc0 .LBB0_480

; #define SBAR() __builtin_amdgcn_sched_barrier(0)
; #define VMW() asm volatile("s_waitcnt vmcnt(0)" ::: "memory")
; #define SWRITE(bf) do { SWRITE_V(bf); SWRITE_K(bf); } while (0)
; #define lane lane_id()
; template <bool ROPE, bool ALIBI, int QP, int Q2P, int KP, int VP, int OP>
; __device__ __forceinline__ void attn_unit(const Unit& u, char* lds, const int wid) {
;     ...
;     bf16x8 qr[8]; const char* q2l = lds + OFF_Q2 + wid * 4096 + lane * 16;
; #pragma unroll
;     for (int d0 = 0; d0 < 8; ++d0) { const bf16x8 qv = *(const bf16x8*)(u.Q + (size_t)(wid * QBLK + r32) * QP + d0 * 16 + hi * 8);
;         if (ALIBI && d0 >= 6) *(bf16x8*)(lds + OFF_Q2 + wid * 4096 + lane * 16 + (d0 - 6) * 1024) = qv; else qr[d0] = qv; }
;     if constexpr (ROPE) {
; #pragma unroll
;         for (int e = 0; e < 4; ++e) *(bf16x8*)(lds + OFF_Q2 + wid * 4096 + lane * 16 + e * 1024) = *(const bf16x8*)(u.Q2 + (size_t)(wid * QBLK + r32) * Q2P + e * 16 + hi * 8);
;     }
;     ...
;     if (wid >= 4) __builtin_amdgcn_s_setprio(1);
;     SLOAD(0); VMW(); SWRITE(0); SBAR();
;     SLOAD(1);
;     __syncthreads();
.LBB0_693:
	s_and_b32 s9, s71, 15
	s_bfe_u32 s4, s71, 0x20008
	s_bfe_u32 s88, s71, 0x40004
	s_lshl_b32 s17, s4, 12
	s_lshl_b32 s5, s9, 8
	s_or_b32 s89, s17, s5
	s_lshl_b32 s5, s88, 14
	s_mul_i32 s6, s88, 0x8200
	s_or_b32 s5, s89, s5
	s_add_i32 s16, s6, 0x4100
	s_lshl_b32 s7, s5, 8
	v_readlane_b32 s35, v254, 5
	s_add_u32 s52, s35, s7
	v_readlane_b32 s7, v254, 25
	v_mbcnt_lo_u32_b32 v75, -1, 0
	v_mbcnt_hi_u32_b32 v75, -1, v75
	v_readlane_b32 s56, v254, 10
	v_and_b32_e32 v74, 31, v75
	v_ashrrev_i32_e32 v18, 5, v75
	s_addc_u32 s53, s7, 0
	s_lshl_b32 s5, s5, 7
	v_or_b32_e32 v20, s56, v74
	v_mov_b32_e32 v21, v2
	v_lshlrev_b32_e32 v6, 3, v18
	s_add_u32 s54, s38, s5
	v_lshlrev_b64 v[4:5], 8, v[20:21]
	v_ashrrev_i32_e32 v7, 31, v6
	s_addc_u32 s55, s39, 0
	v_lshl_add_u64 v[4:5], s[52:53], 0, v[4:5]
	v_lshlrev_b64 v[22:23], 1, v[6:7]
	v_lshlrev_b64 v[20:21], 7, v[20:21]
	v_lshl_add_u64 v[24:25], v[4:5], 0, v[22:23]
	v_lshl_add_u64 v[20:21], s[54:55], 0, v[20:21]
	global_load_dwordx4 v[4:7], v[24:25], off
	global_load_dwordx4 v[8:11], v[24:25], off offset:32
	global_load_dwordx4 v[12:15], v[24:25], off offset:64
	global_load_dwordx4 v[114:117], v[24:25], off offset:96
	global_load_dwordx4 v[118:121], v[24:25], off offset:128
	global_load_dwordx4 v[122:125], v[24:25], off offset:160
	global_load_dwordx4 v[126:129], v[24:25], off offset:192
	global_load_dwordx4 v[130:133], v[24:25], off offset:224
	v_lshl_add_u64 v[24:25], v[20:21], 0, v[22:23]
	global_load_dwordx4 v[44:47], v[24:25], off
	global_load_dwordx4 v[48:51], v[24:25], off offset:32
	global_load_dwordx4 v[52:55], v[24:25], off offset:64
	global_load_dwordx4 v[56:59], v[24:25], off offset:96
	v_lshlrev_b32_e32 v0, 4, v75
	v_add_u32_e32 v17, s82, v0
	s_and_b64 vcc, exec, s[2:3]
	v_readlane_b32 s57, v254, 11
	s_cbranch_vccnz .LBB0_695
	s_setprio 1
.LBB0_695:
	s_lshl_b32 s4, s4, 6
	s_or_b32 s35, s4, 0x4000
	s_add_i32 s4, s6, s17
	s_lshl_b32 s42, s4, 8
	s_add_u32 s4, s78, s42
	s_addc_u32 s5, s79, 0
	s_add_i32 s6, s35, s6
	s_lshl_b32 s6, s6, 8
	s_add_u32 s56, s78, s6
	s_addc_u32 s57, s79, 0
	s_lshl_b32 s6, s17, 7
	s_add_u32 s52, s18, s6
	s_addc_u32 s53, s19, 0
	s_lshl_b32 s40, s35, 7
	v_add_u32_e32 v1, s11, v75
	s_add_u32 s58, s18, s40
	v_ashrrev_i32_e32 v19, 4, v1
	s_addc_u32 s59, s19, 0
	s_add_i32 s17, s16, s17
	v_add_u32_e32 v25, 32, v19
	s_lshl_b32 s17, s17, 8
	v_and_b32_e32 v21, 0xfffff0, v19
	v_lshlrev_b32_e32 v22, 1, v19
	v_and_b32_e32 v26, 0xfffff0, v25
	v_lshlrev_b32_e32 v27, 1, v25
	s_add_u32 s54, s78, s17
	v_lshlrev_b32_e32 v3, 3, v75
	v_and_or_b32 v21, v22, 8, v21
	v_and_or_b32 v26, v27, 8, v26
	s_addc_u32 s55, s79, 0
	s_add_i32 s16, s16, s35
	v_and_b32_e32 v20, 0x78, v3
	v_lshrrev_b32_e32 v22, 1, v19
	v_lshrrev_b32_e32 v21, 1, v21
	v_bfe_u32 v23, v3, 5, 2
	v_and_b32_e32 v24, 3, v19
	v_lshrrev_b32_e32 v26, 1, v26
	s_lshl_b32 s16, s16, 8
	v_or_b32_e32 v21, v21, v23
	v_and_or_b32 v22, v22, 4, v24
	v_lshlrev_b32_e32 v20, 1, v20
	v_or_b32_e32 v23, v26, v23
	s_add_u32 s60, s78, s16
	v_lshlrev_b32_e32 v22, 6, v22
	v_and_b32_e32 v24, 48, v20
	v_lshlrev_b32_e32 v23, 9, v23
	s_addc_u32 s61, s79, 0
	s_lshl_b32 s9, s9, 2
	v_or3_b32 v40, v23, v22, v24
	v_and_b32_e32 v23, 0x70, v1
	v_lshlrev_b32_e32 v26, 4, v1
	v_and_b32_e32 v27, 0x70, v0
	v_bitop3_b32 v1, v0, v1, s97 bitop3:0x28
	v_and_b32_e32 v0, 0xc0, v0
	v_lshlrev_b32_e32 v28, 1, v75
	v_and_or_b32 v0, v3, 24, v0
	v_and_b32_e32 v28, 32, v28
	v_and_b32_e32 v3, 0x100, v3
	s_cmp_lg_u32 0, -1
	v_or3_b32 v0, v0, v28, v3
	s_cselect_b32 s16, 0, 0
	v_add_u32_e32 v3, s16, v0
	v_lshlrev_b32_e32 v0, 8, v19
	v_and_b32_e32 v19, 0xffffff80, v26
	v_lshlrev_b32_e32 v21, 9, v21
	v_lshl_or_b32 v70, v25, 8, v20
	v_or_b32_e32 v72, v0, v20
	v_bitop3_b32 v42, v20, v0, v23 bitop3:0xde
	v_or_b32_e32 v0, v19, v27
	v_or3_b32 v41, v21, v22, v24
	global_load_dwordx4 v[20:23], v72, s[60:61]
	global_load_dwordx4 v[24:27], v70, s[60:61]
	global_load_dwordx4 v[28:31], v72, s[56:57]
	global_load_dwordx4 v[32:35], v70, s[56:57]
	global_load_dwordx4 v[36:39], v0, s[58:59]
	s_waitcnt vmcnt(0)
	ds_write_b128 v17, v[44:47]
	ds_write_b128 v17, v[48:51] offset:1024
	ds_write_b128 v17, v[52:55] offset:2048
	ds_write_b128 v17, v[56:59] offset:3072
	s_add_i32 s45, s80, s9
	v_or_b32_e32 v188, v19, v1
	s_mov_b32 s92, -1
	s_add_i32 s45, s45, 1
	v_mov_b32_e32 v73, v2
	v_mov_b32_e32 v71, v2
	v_mov_b32_e32 v1, v2
	v_add_u32_e32 v189, 0, v41
	v_add_u32_e32 v190, 0, v40
	v_add_u32_e32 v191, 0, v42
	v_add_u32_e32 v19, s96, v188
	s_mov_b32 s7, s43
	s_waitcnt vmcnt(4)
	ds_write_b128 v189, v[20:23]
	s_waitcnt vmcnt(3)
	ds_write_b128 v190, v[24:27]
	s_waitcnt vmcnt(2)
	ds_write_b128 v191, v[28:31] offset:32768
	s_waitcnt vmcnt(1)
	ds_write_b128 v191, v[32:35] offset:40960
	s_waitcnt vmcnt(0)
	ds_write_b128 v19, v[36:39]
	global_load_dwordx4 v[54:57], v72, s[54:55]
	global_load_dwordx4 v[58:61], v70, s[54:55]
	global_load_dwordx4 v[62:65], v72, s[4:5]
	global_load_dwordx4 v[66:69], v70, s[4:5]
	global_load_dwordx4 v[50:53], v0, s[52:53]
	s_waitcnt lgkmcnt(0)
	s_barrier
; #define SBAR() __builtin_amdgcn_sched_barrier(0)
; #define VMW() asm volatile("s_waitcnt vmcnt(0)" ::: "memory")
; #define SWRITE(bf) do { SWRITE_V(bf); SWRITE_K(bf); } while (0)
; template <bool NAT>
; __device__ __forceinline__ void partialSM(f32x16& p0, f32x16& p1, float& m_reg, float& mn, float& alpha) {
;     float pmax = p0[0]; for (int r = 1; r < 16; ++r) pmax = fmaxf(pmax, p0[r]); for (int r = 0; r < 16; ++r) pmax = fmaxf(pmax, p1[r]);
;     { auto rr = __builtin_amdgcn_permlane32_swap(__float_as_uint(pmax), __float_as_uint(pmax), false, false);
;       pmax = fmaxf(__uint_as_float(rr[0]), __uint_as_float(rr[1])); }
;     constexpr float C2 = 1.4426950408889634f;
;     if constexpr (NAT) {
;         if (__builtin_expect(__all((pmax - m_reg) <= 8.f), 1)) { mn = m_reg; alpha = 1.f; }
;         else { mn = fmaxf(m_reg, pmax); alpha = __builtin_amdgcn_exp2f((m_reg - mn) * C2); m_reg = mn; }
;         const float mnL = -mn * C2;
;         for (int r = 0; r < 16; ++r) p0[r] = fmaf(p0[r], C2, mnL); for (int r = 0; r < 16; ++r) p1[r] = fmaf(p1[r], C2, mnL);
;     } else {
;         if (__builtin_expect(__all((pmax - m_reg) <= THR2), 1)) { mn = m_reg; alpha = 1.f; }
;         else { mn = fmaxf(m_reg, pmax); alpha = __builtin_amdgcn_exp2f(m_reg - mn); m_reg = mn; }
;         for (int r = 0; r < 16; ++r) p0[r] = p0[r] - mn; for (int r = 0; r < 16; ++r) p1[r] = p1[r] - mn;
;     }
;     for (int r = 0; r < 16; ++r) p0[r] = __builtin_amdgcn_exp2f(p0[r]);
; template <bool ROPE, bool ALIBI, int QP, int Q2P, int KP, int VP, int OP>
; __device__ __forceinline__ void attn_unit(const Unit& u, char* lds, const int wid) {
;     ...
;     SBAR(); { KAUG(0, ka0_, ka1_); qkt<0, ROPE, ALIBI, ALIBI>(pA0, pA1, K_lds, K2_lds, r32, hi, qr, q2l, ka0_, ka1_, qa); }
;     { const float NEG = -__builtin_inff();
; #pragma unroll
;       for (int r = 8; r < 16; ++r) pA0[r] = NEG;
; #pragma unroll
;       for (int r = 0; r < 16; ++r) pA1[r] = NEG; }
;     BIAS(pA0, pA1, 0); partialSM<ALIBI>(pA0, pA1, m_reg, mnA, alA);
;     VMW(); SWRITE(1);
;     __syncthreads();
	v_lshlrev_b32_e32 v192, 4, v18
	v_lshlrev_b32_e32 v18, 4, v74
	v_and_b32_e32 v18, 0x70, v18
	v_lshlrev_b32_e32 v19, 8, v74
	v_xad_u32 v20, v18, v192, 0
	v_add_u32_e32 v193, v20, v19
	ds_read_b128 v[34:37], v193 offset:32768
	v_add_u32_e32 v84, 32, v192
	v_xad_u32 v20, v84, v18, 0
	v_add_u32_e32 v194, v20, v19
	ds_read_b128 v[76:79], v194 offset:32768
	v_add_u32_e32 v85, 64, v192
	v_xad_u32 v20, v85, v18, 0
	s_waitcnt lgkmcnt(1)
	v_mfma_f32_32x32x16_bf16 v[34:49], v[34:37], v[4:7], 0
	v_add_u32_e32 v195, v20, v19
	v_add_u32_e32 v86, 0x60, v192
	v_xad_u32 v18, v86, v18, 0
	v_add_u32_e32 v196, v18, v19
	v_lshlrev_b32_e32 v87, 7, v74
	v_lshlrev_b32_e32 v88, 3, v74
	v_add_u32_e32 v89, s96, v87
	s_waitcnt lgkmcnt(0)
	v_mfma_f32_32x32x16_bf16 v[34:49], v[76:79], v[8:11], v[34:49]
	ds_read_b128 v[76:79], v195 offset:32768
	v_bitop3_b32 v197, v88, v192, s97 bitop3:0x6c
	v_add_u32_e32 v198, v89, v197
	v_bitop3_b32 v199, v84, v88, s97 bitop3:0x78
	v_add_u32_e32 v200, v89, v199
	v_bitop3_b32 v201, v85, v88, s97 bitop3:0x78
	v_add_u32_e32 v202, v89, v201
	s_waitcnt lgkmcnt(0)
	v_mfma_f32_32x32x16_bf16 v[34:49], v[76:79], v[12:15], v[34:49]
	ds_read_b128 v[76:79], v196 offset:32768
	v_bitop3_b32 v203, v86, v88, s97 bitop3:0x78
	v_add_u32_e32 v204, v89, v203
	s_mov_b32 s4, 0xff800000
	s_mov_b32 s52, s43
	s_mov_b32 s53, s43
	s_mov_b32 s54, s43
	s_waitcnt lgkmcnt(0)
	v_mfma_f32_32x32x16_bf16 v[34:49], v[76:79], v[114:117], v[34:49]
	ds_read_b128 v[76:79], v193 offset:32896
	s_mov_b32 s55, s43
	s_mov_b32 s56, s43
	s_mov_b32 s57, s43
	s_mov_b32 s58, s43
	s_mov_b32 s59, s43
	s_mov_b32 s60, s43
	s_waitcnt lgkmcnt(0)
	v_mfma_f32_32x32x16_bf16 v[34:49], v[76:79], v[118:121], v[34:49]
	ds_read_b128 v[76:79], v194 offset:32896
	s_mov_b32 s61, s43
	s_mov_b32 s62, s43
	s_mov_b32 s63, s43
	s_mov_b32 s64, s43
	s_mov_b32 s65, s43
	s_mov_b32 s66, s43
	s_waitcnt lgkmcnt(0)
	v_mfma_f32_32x32x16_bf16 v[34:49], v[76:79], v[122:125], v[34:49]
	ds_read_b128 v[76:79], v195 offset:32896
	s_mov_b32 s67, s43
	v_mov_b64_e32 v[18:19], s[52:53]
	v_readlane_b32 s1, v254, 4
	v_mov_b64_e32 v[32:33], s[66:67]
	v_lshl_add_u64 v[0:1], s[6:7], 0, v[0:1]
	v_mov_b64_e32 v[20:21], s[54:55]
	s_waitcnt lgkmcnt(0)
	v_mfma_f32_32x32x16_bf16 v[34:49], v[76:79], v[126:129], v[34:49]
	ds_read_b128 v[76:79], v196 offset:32896
	v_mov_b64_e32 v[22:23], s[56:57]
	v_mov_b64_e32 v[24:25], s[58:59]
	v_mov_b64_e32 v[26:27], s[60:61]
	v_mov_b64_e32 v[28:29], s[62:63]
	v_mov_b64_e32 v[30:31], s[64:65]
	v_lshl_add_u32 v209, v74, 2, s90
	s_waitcnt lgkmcnt(0)
	v_mfma_f32_32x32x16_bf16 v[34:49], v[76:79], v[130:133], v[34:49]
	ds_read_b128 v[76:79], v198
	ds_read_b128 v[80:83], v17
	v_lshl_add_u64 v[174:175], s[42:43], 0, v[72:73]
	v_lshl_add_u64 v[176:177], s[42:43], 0, v[70:71]
	v_add_u32_e32 v207, s1, v87
	v_mov_b32_e32 v206, 0
	s_waitcnt lgkmcnt(0)
	v_mfma_f32_32x32x16_bf16 v[34:49], v[76:79], v[80:83], v[34:49]
	ds_read_b128 v[76:79], v200
	ds_read_b128 v[80:83], v17 offset:1024
	s_waitcnt lgkmcnt(0)
	v_mfma_f32_32x32x16_bf16 v[34:49], v[76:79], v[80:83], v[34:49]
	ds_read_b128 v[76:79], v202
	ds_read_b128 v[80:83], v17 offset:2048
	s_waitcnt lgkmcnt(0)
	v_mfma_f32_32x32x16_bf16 v[34:49], v[76:79], v[80:83], v[34:49]
	ds_read_b128 v[76:79], v204
	ds_read_b128 v[80:83], v17 offset:3072
	s_waitcnt vmcnt(0)
	s_waitcnt vmcnt(4)
	ds_write_b128 v189, v[54:57] offset:16384
	s_waitcnt vmcnt(3)
	ds_write_b128 v190, v[58:61] offset:16384
	s_waitcnt vmcnt(2)
	ds_write_b128 v191, v[62:65] offset:49152
	s_waitcnt vmcnt(1)
	ds_write_b128 v191, v[66:69] offset:57344
	s_waitcnt lgkmcnt(4)
	v_mfma_f32_32x32x16_bf16 v[34:49], v[76:79], v[80:83], v[34:49]
	s_nop 11
	v_max3_f32 v42, v34, v35, v36
	v_max3_f32 v42, v42, v37, v38
	v_max3_f32 v42, v42, v39, v40
	v_max3_f32 v42, v42, v41, s4
	v_mov_b32_e32 v43, v42
	s_nop 1
	v_permlane32_swap_b32_e32 v42, v43
	v_max_f32_e32 v43, v43, v43
	v_max_f32_e32 v42, v42, v42
	v_max_f32_e32 v42, v42, v43
	v_add_f32_e32 v43, 0x7149f2ca, v42
	v_cmp_ge_f32_e32 vcc, s0, v43
	s_cmp_eq_u64 vcc, exec
	s_cselect_b64 vcc, -1, 0
	v_max_f32_e32 v42, 0xf149f2ca, v42
	v_sub_f32_e32 v43, 0xf149f2ca, v42
	v_cndmask_b32_e32 v162, v42, v219, vcc
	v_exp_f32_e32 v43, v43
	v_sub_f32_e32 v134, 0xff800000, v162
	v_sub_f32_e32 v34, v34, v162
	v_sub_f32_e32 v35, v35, v162
	v_sub_f32_e32 v36, v36, v162
	v_sub_f32_e32 v37, v37, v162
	v_sub_f32_e32 v38, v38, v162
	v_sub_f32_e32 v39, v39, v162
	v_sub_f32_e32 v40, v40, v162
	v_sub_f32_e32 v41, v41, v162
	v_exp_f32_e32 v150, v134
	v_exp_f32_e32 v154, v34
	v_exp_f32_e32 v158, v35
	v_exp_f32_e32 v155, v36
	v_exp_f32_e32 v157, v37
	v_exp_f32_e32 v153, v38
	v_exp_f32_e32 v156, v39
	v_exp_f32_e32 v151, v40
	v_exp_f32_e32 v152, v41
	v_add_u32_e32 v34, s1, v188
	s_add_i32 s6, s42, 0x400000
	v_cndmask_b32_e64 v205, v43, 1.0, vcc
	s_waitcnt vmcnt(0)
	ds_write_b128 v34, v[50:53]
	v_cmp_gt_u32_e64 s[4:5], 32, v75
	v_lshl_add_u64 v[170:171], s[6:7], 0, v[72:73]
	v_lshl_add_u64 v[172:173], s[6:7], 0, v[70:71]
	v_mov_b64_e32 v[80:81], v[32:33]
	v_mov_b64_e32 v[64:65], v[32:33]
	v_mov_b64_e32 v[48:49], v[32:33]
	s_or_b32 s35, s9, 3
	s_or_b32 s40, s9, 2
	v_mov_b64_e32 v[78:79], v[30:31]
	v_mov_b64_e32 v[76:77], v[28:29]
	v_mov_b64_e32 v[74:75], v[26:27]
	v_mov_b64_e32 v[72:73], v[24:25]
	v_mov_b64_e32 v[70:71], v[22:23]
	v_mov_b64_e32 v[68:69], v[20:21]
	v_mov_b64_e32 v[66:67], v[18:19]
	v_mov_b64_e32 v[62:63], v[30:31]
	v_mov_b64_e32 v[60:61], v[28:29]
	v_mov_b64_e32 v[58:59], v[26:27]
	v_mov_b64_e32 v[56:57], v[24:25]
	v_mov_b64_e32 v[54:55], v[22:23]
	v_mov_b64_e32 v[52:53], v[20:21]
	v_mov_b64_e32 v[50:51], v[18:19]
	v_mov_b64_e32 v[46:47], v[30:31]
	v_mov_b64_e32 v[44:45], v[28:29]
	v_mov_b64_e32 v[42:43], v[26:27]
	v_mov_b64_e32 v[40:41], v[24:25]
	v_mov_b64_e32 v[38:39], v[22:23]
	v_mov_b64_e32 v[36:37], v[20:21]
	v_mov_b64_e32 v[34:35], v[18:19]
	v_mov_b32_e32 v166, v150
	v_mov_b32_e32 v159, v150
	v_mov_b32_e32 v165, v150
	v_mov_b32_e32 v160, v150
	v_mov_b32_e32 v164, v150
	v_mov_b32_e32 v161, v150
	v_mov_b32_e32 v163, v150
	v_mov_b32_e32 v135, v134
	v_mov_b32_e32 v146, v134
	v_mov_b32_e32 v147, v134
	v_mov_b32_e32 v136, v134
	v_mov_b32_e32 v137, v134
	v_mov_b32_e32 v142, v134
	v_mov_b32_e32 v143, v134
	v_mov_b32_e32 v144, v134
	v_mov_b32_e32 v145, v134
	v_mov_b32_e32 v148, v134
	v_mov_b32_e32 v149, v134
	v_mov_b32_e32 v138, v134
	v_mov_b32_e32 v139, v134
	v_mov_b32_e32 v140, v134
	v_mov_b32_e32 v141, v134
	s_waitcnt lgkmcnt(0)
	s_barrier
